# same load de-serialisation for resid_norm layer 0, prenorm0 and the odd-layer row pass (loads of a block issued together at its top)
# speedup vs baseline: 1.0175x; 1.0061x over previous
; DI int get_bid() { int b = blockIdx.x; asm volatile("" : "+s"(b)); return b; }
; DI unsigned pk2(float a, float b) { f32x2_t f = {a, b}; return __builtin_bit_cast(unsigned, __builtin_convertvector(f, bf16x2_t)); }
; DI void odd_rows(const Params& p, int o) {
;     ...
;   for (int r = get_bid() * 4 + (tid >> 6); r < M_TOK; r += gridDim.x * 4) {
;     const float* z = zq + (size_t)r * 704;
;     float2 qv[3]; float ss = 0.f;
; #pragma unroll
;     for (int i = 0; i < 3; ++i) { qv[i] = *(const float2*)(z + lane * 2 + 128 * i); ss += qv[i].x * qv[i].x + qv[i].y * qv[i].y; }
;     const float4 kv = *(const float4*)(z + 384 + lane * 4);
;     float sk = kv.x * kv.x + kv.y * kv.y + kv.z * kv.z + kv.w * kv.w;
;     const float kr = z[640 + lane];
;     ss = wave_sum(ss); sk = wave_sum(sk);
;     const float rq = rsqrtf(ss * (1.f / 384.f) + 1e-6f);
;     const float rk = rsqrtf(sk * (1.f / 256.f) + 1e-6f);
; #pragma unroll
;     for (int i = 0; i < 3; ++i) {
;       const float2 w = *(const float2*)(qnw + lane * 2 + 128 * i);
;       *(unsigned*)(qn + (size_t)r * 384 + lane * 2 + 128 * i) = pk2(qv[i].x * rq * w.x, qv[i].y * rq * w.y);
;     }
.LBB0_119:
	global_load_dwordx2 v[100:101], v[10:11], off offset:1536
	global_load_dwordx2 v[102:103], v[10:11], off offset:2048
	global_load_dwordx2 v[104:105], v[10:11], off offset:2560
	v_mov_b64_e32 v[2:3], s[84:85]
	s_movk_i32 s4, 0xb00
	v_mad_i64_i32 v[22:23], s[4:5], v6, s4, v[2:3]
	v_lshlrev_b32_e32 v24, 2, v8
	v_mov_b32_e32 v25, v183
	v_lshl_add_u64 v[2:3], v[22:23], 0, v[24:25]
	v_lshl_add_u64 v[26:27], v[22:23], 0, v[182:183]
	global_load_dwordx4 v[2:5], v[2:3], off offset:1536
	s_nop 0
	global_load_dwordx2 v[28:29], v[26:27], off offset:512
	global_load_dwordx2 v[30:31], v[26:27], off
	global_load_dwordx2 v[32:33], v[26:27], off offset:1024
	s_nop 0
	v_mov_b32_e32 v21, v183
	v_lshl_add_u64 v[22:23], v[22:23], 0, v[20:21]
	global_load_dword v21, v[22:23], off offset:2560
	s_mov_b32 s4, 0x3b800000
	s_mov_b32 s5, 0x3b2aaaab
	s_waitcnt vmcnt(6)
	s_waitcnt vmcnt(3)
	v_pk_mul_f32 v[42:43], v[28:29], v[28:29]
	s_waitcnt vmcnt(5)
	s_waitcnt vmcnt(2)
	v_mov_b32_e32 v46, v31
	s_waitcnt vmcnt(4)
	s_waitcnt vmcnt(1)
	v_mov_b32_e32 v47, v33
	v_pk_mul_f32 v[22:23], v[2:3], v[2:3]
	v_mov_b32_e32 v44, v30
	v_mov_b32_e32 v45, v32
	v_pk_mul_f32 v[46:47], v[46:47], v[46:47]
	v_pk_mul_f32 v[26:27], v[4:5], v[4:5]
	v_mov_b32_e32 v48, v22
	v_mov_b32_e32 v49, v42
	v_mov_b32_e32 v42, v23
	v_pk_fma_f32 v[44:45], v[44:45], v[44:45], v[46:47]
	v_mov_b32_e32 v22, v26
	v_pk_add_f32 v[42:43], v[48:49], v[42:43]
	v_mov_b32_e32 v23, v44
	v_mov_b32_e32 v44, v27
	v_pk_add_f32 v[22:23], v[42:43], v[22:23]
	s_nop 0
	v_pk_add_f32 v[22:23], v[22:23], v[44:45]
	v_mov_b32_e32 v26, v22
	v_mov_b32_e32 v27, v23
	s_nop 1
	v_permlane32_swap_b32_e32 v22, v26
	v_permlane32_swap_b32_e32 v23, v27
	s_waitcnt lgkmcnt(0)
	v_pk_add_f32 v[22:23], v[22:23], v[26:27]
	v_mov_b32_e32 v26, v22
	v_mov_b32_e32 v27, v23
	s_nop 1
	v_permlane16_swap_b32_e32 v22, v26
	v_permlane16_swap_b32_e32 v23, v27
	s_waitcnt lgkmcnt(0)
	v_pk_add_f32 v[22:23], v[22:23], v[26:27]
	s_nop 1
	v_mov_b32_dpp v26, v22 row_ror:8 row_mask:0xf bank_mask:0xf
	v_mov_b32_dpp v27, v23 row_ror:8 row_mask:0xf bank_mask:0xf
	s_waitcnt lgkmcnt(0)
	v_pk_add_f32 v[22:23], v[22:23], v[26:27]
	s_nop 1
	v_mov_b32_dpp v26, v22 row_ror:4 row_mask:0xf bank_mask:0xf
	v_mov_b32_dpp v27, v23 row_ror:4 row_mask:0xf bank_mask:0xf
	s_waitcnt lgkmcnt(0)
	v_pk_add_f32 v[22:23], v[22:23], v[26:27]
	s_nop 1
	v_mov_b32_dpp v26, v22 quad_perm:[2,3,0,1] row_mask:0xf bank_mask:0xf
	v_mov_b32_dpp v27, v23 quad_perm:[2,3,0,1] row_mask:0xf bank_mask:0xf
	s_waitcnt lgkmcnt(0)
	v_pk_add_f32 v[22:23], v[22:23], v[26:27]
	s_nop 1
	v_mov_b32_dpp v26, v22 quad_perm:[1,0,3,2] row_mask:0xf bank_mask:0xf
	v_mov_b32_dpp v27, v23 quad_perm:[1,0,3,2] row_mask:0xf bank_mask:0xf
	s_waitcnt lgkmcnt(0)
	v_pk_add_f32 v[22:23], v[22:23], v[26:27]
	s_nop 0
	v_pk_fma_f32 v[26:27], v[22:23], s[4:5], v[184:185] op_sel_hi:[1,1,0]
	s_movk_i32 s4, 0x300
	v_mul_f32_e32 v7, 0x4b800000, v27
	v_cmp_gt_f32_e64 s[38:39], s33, v27
	v_mad_i64_i32 v[22:23], s[4:5], v6, s4, v[12:13]
	s_nop 0
	v_cndmask_b32_e64 v7, v27, v7, s[38:39]
	v_rsq_f32_e32 v7, v7
	s_movk_i32 s4, 0x3fff
	v_cmp_lt_i32_e64 s[40:41], s4, v6
	v_mul_f32_e32 v25, 0x45800000, v7
	v_cndmask_b32_e64 v42, v7, v25, s[38:39]
	v_pk_mul_f32 v[30:31], v[30:31], v[42:43] op_sel_hi:[1,0]
	v_pk_mul_f32 v[28:29], v[28:29], v[42:43] op_sel_hi:[1,0]
	s_waitcnt vmcnt(3)
	v_pk_mul_f32 v[30:31], v[100:101], v[30:31]
	v_cmp_gt_f32_e64 s[38:39], s33, v26
	v_cvt_pk_bf16_f32 v7, v30, v31
	global_store_dword v[22:23], v7, off
	s_nop 0
	s_waitcnt vmcnt(1)
	v_pk_mul_f32 v[28:29], v[102:103], v[28:29]
	s_nop 0
	v_cvt_pk_bf16_f32 v7, v28, v29
	global_store_dword v[22:23], v7, off offset:256
	s_nop 0
	v_pk_mul_f32 v[30:31], v[32:33], v[42:43] op_sel_hi:[1,0]
	v_ashrrev_i32_e32 v7, 31, v6
	s_waitcnt vmcnt(0)
	v_pk_mul_f32 v[28:29], v[30:31], v[104:105]
	s_nop 0
	v_cvt_pk_bf16_f32 v25, v28, v29
	global_store_dword v[22:23], v25, off offset:512
	v_mov_b32_e32 v40, v100
	v_mov_b32_e32 v41, v101
	s_and_saveexec_b64 s[4:5], s[40:41]
	s_xor_b64 s[40:41], exec, s[4:5]
	s_cbranch_execz .LBB0_121
	v_add_u32_e32 v22, 0xffffc000, v6
	v_lshrrev_b32_e32 v22, 5, v22
	s_movk_i32 s4, 0x480
	v_and_b32_e32 v25, 31, v6
	v_mul_lo_u32 v22, v22, s4
	s_movk_i32 s4, 0xc200
	v_or_b32_e32 v22, v22, v25
	s_mov_b32 s5, -1
	v_add_u32_e32 v22, 0x4400, v22
	v_mov_b32_e32 v23, v183
	v_or_b32_e32 v27, 0x400, v25
	v_lshl_add_u64 v[28:29], v[6:7], 0, s[4:5]

; DI int get_bid() { int b = blockIdx.x; asm volatile("" : "+s"(b)); return b; }
; DI unsigned pk2(float a, float b) { f32x2_t f = {a, b}; return __builtin_bit_cast(unsigned, __builtin_convertvector(f, bf16x2_t)); }
; DI void odd_rows(const Params& p, int o) {
;     ...
;   for (int r = get_bid() * 4 + (tid >> 6); r < M_TOK; r += gridDim.x * 4) {
;     const float* z = zq + (size_t)r * 704;
;     float2 qv[3]; float ss = 0.f;
; #pragma unroll
;     for (int i = 0; i < 3; ++i) { qv[i] = *(const float2*)(z + lane * 2 + 128 * i); ss += qv[i].x * qv[i].x + qv[i].y * qv[i].y; }
;     const float4 kv = *(const float4*)(z + 384 + lane * 4);
;     float sk = kv.x * kv.x + kv.y * kv.y + kv.z * kv.z + kv.w * kv.w;
;     const float kr = z[640 + lane];
;     ss = wave_sum(ss); sk = wave_sum(sk);
;     const float rq = rsqrtf(ss * (1.f / 384.f) + 1e-6f);
;     const float rk = rsqrtf(sk * (1.f / 256.f) + 1e-6f);
; #pragma unroll
;     for (int i = 0; i < 3; ++i) {
;       const float2 w = *(const float2*)(qnw + lane * 2 + 128 * i);
;       *(unsigned*)(qn + (size_t)r * 384 + lane * 2 + 128 * i) = pk2(qv[i].x * rq * w.x, qv[i].y * rq * w.y);
;     }
.LBB0_1001:
	global_load_dwordx2 v[100:101], v[8:9], off
	global_load_dwordx2 v[102:103], v[8:9], off offset:512
	global_load_dwordx2 v[104:105], v[8:9], off offset:1024
	v_mov_b64_e32 v[0:1], s[84:85]
	s_movk_i32 s4, 0xb00
	v_mad_i64_i32 v[20:21], s[4:5], v4, s4, v[0:1]
	v_lshlrev_b32_e32 v22, 2, v6
	v_mov_b32_e32 v23, v183
	v_lshl_add_u64 v[0:1], v[20:21], 0, v[22:23]
	v_lshl_add_u64 v[24:25], v[20:21], 0, v[182:183]
	global_load_dwordx4 v[0:3], v[0:1], off offset:1536
	s_nop 0
	global_load_dwordx2 v[26:27], v[24:25], off offset:512
	global_load_dwordx2 v[28:29], v[24:25], off
	global_load_dwordx2 v[30:31], v[24:25], off offset:1024
	s_nop 0
	v_mov_b32_e32 v19, v183
	v_lshl_add_u64 v[20:21], v[20:21], 0, v[18:19]
	global_load_dword v19, v[20:21], off offset:2560
	s_mov_b32 s4, 0x3b800000
	s_mov_b32 s5, 0x3b2aaaab
	s_waitcnt vmcnt(6)
	s_waitcnt vmcnt(3)
	v_pk_mul_f32 v[42:43], v[26:27], v[26:27]
	s_waitcnt vmcnt(5)
	s_waitcnt vmcnt(2)
	v_mov_b32_e32 v46, v29
	s_waitcnt vmcnt(4)
	s_waitcnt vmcnt(1)
	v_mov_b32_e32 v47, v31
	v_pk_mul_f32 v[20:21], v[0:1], v[0:1]
	v_mov_b32_e32 v44, v28
	v_mov_b32_e32 v45, v30
	v_pk_mul_f32 v[46:47], v[46:47], v[46:47]
	v_pk_mul_f32 v[24:25], v[2:3], v[2:3]
	v_mov_b32_e32 v48, v20
	v_mov_b32_e32 v49, v42
	v_mov_b32_e32 v42, v21
	v_pk_fma_f32 v[44:45], v[44:45], v[44:45], v[46:47]
	v_mov_b32_e32 v20, v24
	v_pk_add_f32 v[42:43], v[48:49], v[42:43]
	v_mov_b32_e32 v21, v44
	v_mov_b32_e32 v44, v25
	v_pk_add_f32 v[20:21], v[42:43], v[20:21]
	s_nop 0
	v_pk_add_f32 v[20:21], v[20:21], v[44:45]
	v_mov_b32_e32 v24, v20
	v_mov_b32_e32 v25, v21
	s_nop 1
	v_permlane32_swap_b32_e32 v20, v24
	v_permlane32_swap_b32_e32 v21, v25
	s_waitcnt lgkmcnt(0)
	v_pk_add_f32 v[20:21], v[20:21], v[24:25]
	v_mov_b32_e32 v24, v20
	v_mov_b32_e32 v25, v21
	s_nop 1
	v_permlane16_swap_b32_e32 v20, v24
	v_permlane16_swap_b32_e32 v21, v25
	s_waitcnt lgkmcnt(0)
	v_pk_add_f32 v[20:21], v[20:21], v[24:25]
	s_nop 1
	v_mov_b32_dpp v24, v20 row_ror:8 row_mask:0xf bank_mask:0xf
	v_mov_b32_dpp v25, v21 row_ror:8 row_mask:0xf bank_mask:0xf
	s_waitcnt lgkmcnt(0)
	v_pk_add_f32 v[20:21], v[20:21], v[24:25]
	s_nop 1
	v_mov_b32_dpp v24, v20 row_ror:4 row_mask:0xf bank_mask:0xf
	v_mov_b32_dpp v25, v21 row_ror:4 row_mask:0xf bank_mask:0xf
	s_waitcnt lgkmcnt(0)
	v_pk_add_f32 v[20:21], v[20:21], v[24:25]
	s_nop 1
	v_mov_b32_dpp v24, v20 quad_perm:[2,3,0,1] row_mask:0xf bank_mask:0xf
	v_mov_b32_dpp v25, v21 quad_perm:[2,3,0,1] row_mask:0xf bank_mask:0xf
	s_waitcnt lgkmcnt(0)
	v_pk_add_f32 v[20:21], v[20:21], v[24:25]
	s_nop 1
	v_mov_b32_dpp v24, v20 quad_perm:[1,0,3,2] row_mask:0xf bank_mask:0xf
	v_mov_b32_dpp v25, v21 quad_perm:[1,0,3,2] row_mask:0xf bank_mask:0xf
	s_waitcnt lgkmcnt(0)
	v_pk_add_f32 v[20:21], v[20:21], v[24:25]
	s_nop 0
	v_pk_fma_f32 v[24:25], v[20:21], s[4:5], v[184:185] op_sel_hi:[1,1,0]
	s_movk_i32 s4, 0x300
	v_mul_f32_e32 v5, 0x4b800000, v25
	v_cmp_gt_f32_e64 s[38:39], s33, v25
	v_mad_i64_i32 v[20:21], s[4:5], v4, s4, v[10:11]
	s_nop 0
	v_cndmask_b32_e64 v5, v25, v5, s[38:39]
	v_rsq_f32_e32 v5, v5
	s_movk_i32 s4, 0x3fff
	v_cmp_lt_i32_e64 s[40:41], s4, v4
	v_mul_f32_e32 v23, 0x45800000, v5
	v_cndmask_b32_e64 v42, v5, v23, s[38:39]
	v_pk_mul_f32 v[28:29], v[28:29], v[42:43] op_sel_hi:[1,0]
	v_pk_mul_f32 v[26:27], v[26:27], v[42:43] op_sel_hi:[1,0]
	s_waitcnt vmcnt(3)
	v_pk_mul_f32 v[28:29], v[100:101], v[28:29]
	v_cmp_gt_f32_e64 s[38:39], s33, v24
	v_cvt_pk_bf16_f32 v5, v28, v29
	global_store_dword v[20:21], v5, off
	s_nop 0
	s_waitcnt vmcnt(1)
	v_pk_mul_f32 v[26:27], v[102:103], v[26:27]
	s_nop 0
	v_cvt_pk_bf16_f32 v5, v26, v27
	global_store_dword v[20:21], v5, off offset:256
	s_nop 0
	v_pk_mul_f32 v[28:29], v[30:31], v[42:43] op_sel_hi:[1,0]
	v_ashrrev_i32_e32 v5, 31, v4
	s_waitcnt vmcnt(0)
	v_pk_mul_f32 v[26:27], v[28:29], v[104:105]
	s_nop 0
	v_cvt_pk_bf16_f32 v23, v26, v27
	global_store_dword v[20:21], v23, off offset:512
	v_mov_b32_e32 v40, v100
	v_mov_b32_e32 v41, v101
	s_and_saveexec_b64 s[4:5], s[40:41]
	s_xor_b64 s[40:41], exec, s[4:5]
	s_cbranch_execz .LBB0_1003
	v_add_u32_e32 v26, 0xffffc000, v4
	v_lshrrev_b32_e32 v5, 5, v26
	s_movk_i32 s4, 0x480
	v_and_b32_e32 v23, 31, v4
	v_mul_lo_u32 v5, v5, s4
	v_or_b32_e32 v5, v5, v23
	v_add_u32_e32 v20, 0x4400, v5
	v_mov_b32_e32 v21, v183
	v_or_b32_e32 v25, 0x400, v23
	v_mov_b32_e32 v27, v183

; DI int get_tid() { int t = threadIdx.x; asm volatile("" : "+v"(t)); return t; }
; DI int get_bid() { int b = blockIdx.x; asm volatile("" : "+s"(b)); return b; }
; DI float bflo(unsigned u) { return __uint_as_float(u << 16); }
; DI float bfhi(unsigned u) { return __uint_as_float(u & 0xffff0000u); }
; DI void resid_norm(const Params& p, int layer, const u16* __restrict__ y) {
;     ...
;   for (int r = get_bid() * 4 + (get_tid() >> 6); r < M_TOK; r += gridDim.x * 4) {
;     const float* x;
;     if (layer == 0) x = r < M_PROMPT ? p.x_prompt + (size_t)r * 1024 : p.x_sample + (size_t)(r - M_PROMPT) * 1024;
;     else x = p.out + (size_t)r * 1024;
;     float4 yv[4], xv[4]; float ss = 0.f;
; #pragma unroll
;     for (int i = 0; i < 4; ++i) {
;       { const uint2 yq = *(const uint2*)(y + (size_t)r * 1024 + lane * 4 + 256 * i); yv[i] = make_float4(bflo(yq.x), bfhi(yq.x), bflo(yq.y), bfhi(yq.y)); }
;       { const f32x4 t4 = __builtin_nontemporal_load((const f32x4*)(x + lane * 4 + 256 * i)); xv[i] = make_float4(t4[0], t4[1], t4[2], t4[3]); }
;       ss += yv[i].x * yv[i].x + yv[i].y * yv[i].y + yv[i].z * yv[i].z + yv[i].w * yv[i].w;
;     }
;     ss = wave_sum(ss);
;     const float rs = rsqrtf(ss * (1.f / 1024.f) + 1e-6f);
;     float ss2 = 0.f;
; #pragma unroll
;     for (int i = 0; i < 4; ++i) {
;       const float4 gg = *(const float4*)(gpost + lane * 4 + 256 * i);
;       xv[i].x += yv[i].x * rs * gg.x; xv[i].y += yv[i].y * rs * gg.y; xv[i].z += yv[i].z * rs * gg.z; xv[i].w += yv[i].w * rs * gg.w;
;       __builtin_nontemporal_store((f32x4){xv[i].x, xv[i].y, xv[i].z, xv[i].w}, (f32x4*)(p.out + (size_t)r * 1024 + lane * 4 + 256 * i));
;       ss2 += xv[i].x * xv[i].x + xv[i].y * xv[i].y + xv[i].z * xv[i].z + xv[i].w * xv[i].w;
.LBB0_1267:
	s_or_b64 exec, exec, s[42:43]
	v_lshlrev_b64 v[100:101], 11, v[0:1]
	v_lshl_add_u64 v[102:103], v[2:3], 0, v[100:101]
	global_load_dwordx2 v[104:105], v[102:103], off
	global_load_dwordx2 v[106:107], v[102:103], off offset:512
	global_load_dwordx2 v[108:109], v[102:103], off offset:1024
	global_load_dwordx2 v[110:111], v[102:103], off offset:1536
	v_lshl_add_u64 v[112:113], v[16:17], 0, v[182:183]
	global_load_dwordx4 v[114:117], v[4:5], off
	global_load_dwordx4 v[118:121], v[112:113], off nt
	global_load_dwordx4 v[122:125], v[112:113], off offset:1024 nt
	global_load_dwordx4 v[126:129], v[112:113], off offset:2048 nt
	global_load_dwordx4 v[130:133], v[112:113], off offset:3072 nt
	global_load_dwordx4 v[134:137], v[4:5], off offset:1024
	global_load_dwordx4 v[138:141], v[4:5], off offset:2048
	global_load_dwordx4 v[142:145], v[4:5], off offset:3072
	global_load_dwordx4 v[146:149], v[6:7], off
	global_load_dwordx4 v[150:153], v[6:7], off offset:1024
	global_load_dwordx4 v[154:157], v[6:7], off offset:2048
	global_load_dwordx4 v[158:161], v[6:7], off offset:3072
	s_nop 0
	s_nop 0
	s_nop 0
	s_nop 0
	s_nop 0
	s_nop 0
	s_nop 0
	s_nop 0
	s_nop 0
	v_add_u32_e32 v0, s3, v0
	s_waitcnt vmcnt(15)
	v_and_b32_e32 v43, 0xffff0000, v104
	s_waitcnt vmcnt(14)
	v_and_b32_e32 v47, 0xffff0000, v106
	v_lshlrev_b32_e32 v42, 16, v104
	v_lshlrev_b32_e32 v44, 16, v105
	v_and_b32_e32 v45, 0xffff0000, v105
	v_lshlrev_b32_e32 v46, 16, v106
	s_waitcnt vmcnt(13)
	v_and_b32_e32 v51, 0xffff0000, v108
	s_waitcnt vmcnt(12)
	v_and_b32_e32 v55, 0xffff0000, v110
	v_mov_b32_e32 v32, v43
	v_mov_b32_e32 v33, v47
	v_lshlrev_b32_e32 v48, 16, v107
	v_lshlrev_b32_e32 v50, 16, v108
	v_lshlrev_b32_e32 v54, 16, v110
	v_mov_b32_e32 v16, v42
	v_mov_b32_e32 v17, v46
	v_mov_b32_e32 v58, v51
	v_mov_b32_e32 v59, v55
	v_pk_mul_f32 v[32:33], v[32:33], v[32:33]
	v_and_b32_e32 v49, 0xffff0000, v107
	v_lshlrev_b32_e32 v52, 16, v109
	v_lshlrev_b32_e32 v56, 16, v111
	v_and_b32_e32 v57, 0xffff0000, v111
	v_mov_b32_e32 v34, v44
	v_mov_b32_e32 v35, v48
	v_mov_b32_e32 v38, v50
	v_mov_b32_e32 v39, v54
	v_pk_mul_f32 v[58:59], v[58:59], v[58:59]
	v_pk_fma_f32 v[16:17], v[16:17], v[16:17], v[32:33]
	v_and_b32_e32 v53, 0xffff0000, v109
	v_mov_b32_e32 v36, v45
	v_mov_b32_e32 v37, v49
	v_mov_b32_e32 v60, v52
	v_mov_b32_e32 v61, v56
	v_pk_fma_f32 v[32:33], v[38:39], v[38:39], v[58:59]
	v_pk_fma_f32 v[16:17], v[34:35], v[34:35], v[16:17]
	v_mov_b32_e32 v62, v53
	v_mov_b32_e32 v63, v57
	v_pk_fma_f32 v[32:33], v[60:61], v[60:61], v[32:33]
	v_pk_fma_f32 v[16:17], v[36:37], v[36:37], v[16:17]
	v_pk_fma_f32 v[32:33], v[62:63], v[62:63], v[32:33]
	v_add_f32_e32 v1, v16, v17
	v_add_f32_e32 v1, v1, v32
	v_add_f32_e32 v1, v1, v33
	v_mov_b32_e32 v16, v1
	s_nop 1
	v_permlane32_swap_b32_e32 v1, v16
	v_lshl_add_u64 v[58:59], v[10:11], 0, v[14:15]
	s_waitcnt lgkmcnt(0)
	v_add_f32_e32 v1, v1, v16
	v_mov_b32_e32 v16, v1
	s_nop 1
	v_permlane16_swap_b32_e32 v1, v16
	s_waitcnt lgkmcnt(0)
	v_add_f32_e32 v1, v1, v16
	s_nop 1
	v_mov_b32_dpp v16, v1 row_ror:8 row_mask:0xf bank_mask:0xf
	s_waitcnt lgkmcnt(0)
	v_add_f32_e32 v1, v1, v16
	s_nop 1
	v_mov_b32_dpp v16, v1 row_ror:4 row_mask:0xf bank_mask:0xf
	s_waitcnt lgkmcnt(0)
	v_add_f32_e32 v1, v1, v16
	s_nop 1
	v_mov_b32_dpp v16, v1 quad_perm:[2,3,0,1] row_mask:0xf bank_mask:0xf
	s_waitcnt lgkmcnt(0)
	v_add_f32_e32 v1, v1, v16
	s_nop 1
	v_mov_b32_dpp v16, v1 quad_perm:[1,0,3,2] row_mask:0xf bank_mask:0xf
	s_waitcnt lgkmcnt(0)
	v_add_f32_e32 v1, v1, v16
	v_fmamk_f32 v1, v1, 0x3a800000, v184
	v_mul_f32_e32 v14, 0x4b800000, v1
	v_cmp_gt_f32_e32 vcc, s33, v1
	s_nop 1
	v_cndmask_b32_e32 v1, v1, v14, vcc
	v_rsq_f32_e32 v1, v1
	s_nop 0
	s_nop 0
	s_nop 0
	v_mul_f32_e32 v40, 0x45800000, v1
	v_cndmask_b32_e32 v40, v1, v40, vcc
	v_mov_b32_e32 v162, v40
	v_mov_b32_e32 v163, v113
	v_pk_mul_f32 v[42:43], v[162:163], v[42:43] op_sel_hi:[0,1]
	v_mov_b32_e32 v164, v40
	v_mov_b32_e32 v165, v113
	v_pk_mul_f32 v[44:45], v[164:165], v[44:45] op_sel_hi:[0,1]
	s_waitcnt vmcnt(10)
	v_pk_fma_f32 v[24:25], v[114:115], v[42:43], v[118:119]
	v_pk_fma_f32 v[26:27], v[116:117], v[44:45], v[120:121]
	global_store_dwordx4 v[58:59], v[24:27], off nt
	s_nop 0
	v_mov_b32_e32 v166, v40
	v_mov_b32_e32 v167, v113
	v_pk_mul_f32 v[42:43], v[166:167], v[46:47] op_sel_hi:[0,1]
	v_mov_b32_e32 v168, v40
	v_mov_b32_e32 v169, v113
	v_pk_mul_f32 v[44:45], v[168:169], v[48:49] op_sel_hi:[0,1]
	v_mov_b32_e32 v46, v27
	s_waitcnt vmcnt(6)
; DI void st_bf4(u16* p, float a, float b, float c, float d) { *(uint2*)p = make_uint2(pk2(a, b), pk2(c, d)); }
; DI void resid_norm(const Params& p, int layer, const u16* __restrict__ y) {
;     ...
; #pragma unroll
;     for (int i = 0; i < 4; ++i) {
;       const float4 gg = *(const float4*)(gpost + lane * 4 + 256 * i);
;       xv[i].x += yv[i].x * rs * gg.x; xv[i].y += yv[i].y * rs * gg.y; xv[i].z += yv[i].z * rs * gg.z; xv[i].w += yv[i].w * rs * gg.w;
;       __builtin_nontemporal_store((f32x4){xv[i].x, xv[i].y, xv[i].z, xv[i].w}, (f32x4*)(p.out + (size_t)r * 1024 + lane * 4 + 256 * i));
;       ss2 += xv[i].x * xv[i].x + xv[i].y * xv[i].y + xv[i].z * xv[i].z + xv[i].w * xv[i].w;
;     }
;     if (layer < 3) {
;       ss2 = wave_sum(ss2);
;       const float rs2 = rsqrtf(ss2 * (1.f / 1024.f) + 1e-6f);
; #pragma unroll
;       for (int i = 0; i < 4; ++i) {
;         const float4 gg = *(const float4*)(gpre + lane * 4 + 256 * i);
;         st_bf4(h + (size_t)r * 1024 + lane * 4 + 256 * i, xv[i].x * rs2 * gg.x, xv[i].y * rs2 * gg.y, xv[i].z * rs2 * gg.z, xv[i].w * rs2 * gg.w);
;       }
	v_pk_fma_f32 v[14:15], v[134:135], v[42:43], v[122:123]
	v_pk_fma_f32 v[16:17], v[136:137], v[44:45], v[124:125]
	global_store_dwordx4 v[58:59], v[14:17], off offset:1024 nt
	s_nop 0
	v_mov_b32_e32 v170, v40
	v_mov_b32_e32 v171, v113
	v_pk_mul_f32 v[42:43], v[170:171], v[50:51] op_sel_hi:[0,1]
	v_mov_b32_e32 v172, v40
	v_mov_b32_e32 v173, v113
	v_pk_mul_f32 v[44:45], v[172:173], v[52:53] op_sel_hi:[0,1]
	v_mov_b32_e32 v47, v17
	s_waitcnt vmcnt(5)
	v_pk_fma_f32 v[28:29], v[138:139], v[42:43], v[126:127]
	v_pk_fma_f32 v[30:31], v[44:45], v[140:141], v[128:129]
	global_store_dwordx4 v[58:59], v[28:31], off offset:2048 nt
	s_nop 0
	v_mov_b32_e32 v174, v40
	v_mov_b32_e32 v175, v113
	v_pk_mul_f32 v[42:43], v[174:175], v[54:55] op_sel_hi:[0,1]
	v_mov_b32_e32 v176, v40
	v_mov_b32_e32 v177, v113
	v_pk_mul_f32 v[40:41], v[176:177], v[56:57] op_sel_hi:[0,1]
	v_mov_b32_e32 v44, v26
	v_mov_b32_e32 v45, v16
	s_waitcnt vmcnt(4)
	v_pk_fma_f32 v[32:33], v[42:43], v[142:143], v[130:131]
	v_pk_fma_f32 v[34:35], v[40:41], v[144:145], v[132:133]
	global_store_dwordx4 v[58:59], v[32:35], off offset:3072 nt
	s_nop 0
	v_mov_b32_e32 v42, v25
	v_mov_b32_e32 v43, v15
	v_mov_b32_e32 v40, v24
	v_mov_b32_e32 v41, v14
	v_pk_mul_f32 v[42:43], v[42:43], v[42:43]
	s_nop 0
	v_pk_fma_f32 v[40:41], v[40:41], v[40:41], v[42:43]
	v_mov_b32_e32 v42, v29
	v_pk_fma_f32 v[40:41], v[44:45], v[44:45], v[40:41]
	v_mov_b32_e32 v43, v33
	v_pk_fma_f32 v[40:41], v[46:47], v[46:47], v[40:41]
	v_pk_mul_f32 v[42:43], v[42:43], v[42:43]
	v_add_f32_e32 v1, v40, v41
	v_mov_b32_e32 v40, v28
	v_mov_b32_e32 v41, v32
	v_mov_b32_e32 v44, v30
	v_mov_b32_e32 v45, v34
	v_pk_fma_f32 v[40:41], v[40:41], v[40:41], v[42:43]
	v_mov_b32_e32 v46, v31
	v_mov_b32_e32 v47, v35
	v_pk_fma_f32 v[40:41], v[44:45], v[44:45], v[40:41]
	s_nop 0
	v_pk_fma_f32 v[40:41], v[46:47], v[46:47], v[40:41]
	s_nop 0
	v_add_f32_e32 v1, v40, v1
	v_add_f32_e32 v1, v1, v41
	v_mov_b32_e32 v40, v1
	s_nop 1
	v_permlane32_swap_b32_e32 v1, v40
	s_waitcnt lgkmcnt(0)
	v_add_f32_e32 v1, v1, v40
	v_mov_b32_e32 v40, v1
	s_nop 1
	v_permlane16_swap_b32_e32 v1, v40
	s_waitcnt lgkmcnt(0)
	v_add_f32_e32 v1, v1, v40
	s_nop 1
	v_mov_b32_dpp v40, v1 row_ror:8 row_mask:0xf bank_mask:0xf
	s_waitcnt lgkmcnt(0)
	v_add_f32_e32 v1, v1, v40
	s_nop 1
	v_mov_b32_dpp v40, v1 row_ror:4 row_mask:0xf bank_mask:0xf
	s_waitcnt lgkmcnt(0)
	v_add_f32_e32 v1, v1, v40
	s_nop 1
	v_mov_b32_dpp v40, v1 quad_perm:[2,3,0,1] row_mask:0xf bank_mask:0xf
	s_waitcnt lgkmcnt(0)
	v_add_f32_e32 v1, v1, v40
	s_nop 1
	v_mov_b32_dpp v40, v1 quad_perm:[1,0,3,2] row_mask:0xf bank_mask:0xf
	s_waitcnt lgkmcnt(0)
	v_add_f32_e32 v1, v1, v40
	v_fmamk_f32 v1, v1, 0x3a800000, v184
	v_mul_f32_e32 v40, 0x4b800000, v1
	v_cmp_gt_f32_e32 vcc, s33, v1
	s_nop 1
	v_cndmask_b32_e32 v1, v1, v40, vcc
	v_rsq_f32_e32 v1, v1
	v_lshl_add_u64 v[40:41], v[8:9], 0, v[100:101]
	v_mul_f32_e32 v12, 0x45800000, v1
	v_cndmask_b32_e32 v42, v1, v12, vcc
	v_pk_mul_f32 v[12:13], v[24:25], v[42:43] op_sel_hi:[1,0]
	v_pk_mul_f32 v[24:25], v[26:27], v[42:43] op_sel_hi:[1,0]
	v_cmp_lt_i32_e32 vcc, s64, v0
	s_or_b64 s[40:41], vcc, s[40:41]
	s_waitcnt vmcnt(3)
	v_pk_mul_f32 v[12:13], v[146:147], v[12:13]
	v_pk_mul_f32 v[24:25], v[148:149], v[24:25]
	v_cvt_pk_bf16_f32 v12, v12, v13
	v_cvt_pk_bf16_f32 v13, v24, v25
	global_store_dwordx2 v[40:41], v[12:13], off
	s_nop 0
	v_pk_mul_f32 v[12:13], v[14:15], v[42:43] op_sel_hi:[1,0]
	v_pk_mul_f32 v[14:15], v[16:17], v[42:43] op_sel_hi:[1,0]
	v_pk_mul_f32 v[16:17], v[28:29], v[42:43] op_sel_hi:[1,0]
	s_waitcnt vmcnt(2)
	v_pk_mul_f32 v[12:13], v[150:151], v[12:13]
	v_pk_mul_f32 v[14:15], v[152:153], v[14:15]
	v_cvt_pk_bf16_f32 v12, v12, v13
	v_cvt_pk_bf16_f32 v13, v14, v15
	global_store_dwordx2 v[40:41], v[12:13], off offset:512
	s_nop 0
	v_pk_mul_f32 v[24:25], v[30:31], v[42:43] op_sel_hi:[1,0]
	s_waitcnt vmcnt(1)
	v_pk_mul_f32 v[12:13], v[16:17], v[154:155]
	v_pk_mul_f32 v[14:15], v[24:25], v[156:157]
	v_cvt_pk_bf16_f32 v12, v12, v13
	v_cvt_pk_bf16_f32 v13, v14, v15
	global_store_dwordx2 v[40:41], v[12:13], off offset:1024
	s_nop 0
	v_pk_mul_f32 v[16:17], v[32:33], v[42:43] op_sel_hi:[1,0]
	v_pk_mul_f32 v[24:25], v[34:35], v[42:43] op_sel_hi:[1,0]
	s_waitcnt vmcnt(0)
	v_pk_mul_f32 v[12:13], v[16:17], v[158:159]
	v_pk_mul_f32 v[14:15], v[24:25], v[160:161]
	v_cvt_pk_bf16_f32 v12, v12, v13
	v_cvt_pk_bf16_f32 v13, v14, v15
	global_store_dwordx2 v[40:41], v[12:13], off offset:1536
	v_mov_b32_e32 v26, v152
	v_mov_b32_e32 v27, v153
	v_mov_b32_e32 v36, v146
	v_mov_b32_e32 v37, v147
	v_mov_b32_e32 v38, v148
	v_mov_b32_e32 v39, v149
	s_andn2_b64 exec, exec, s[40:41]
	s_cbranch_execz .LBB0_1272

; DI int get_tid() { int t = threadIdx.x; asm volatile("" : "+v"(t)); return t; }
; DI int get_bid() { int b = blockIdx.x; asm volatile("" : "+s"(b)); return b; }
; DI void st_bf4(u16* p, float a, float b, float c, float d) { *(uint2*)p = make_uint2(pk2(a, b), pk2(c, d)); }
; DI void prenorm0(const Params& p) {
;     ...
;   for (int r = get_bid() * 4 + (get_tid() >> 6); r < M_TOK; r += gridDim.x * 4) {
;     const float* x = r < M_PROMPT ? p.x_prompt + (size_t)r * 1024 : p.x_sample + (size_t)(r - M_PROMPT) * 1024;
;     float4 v[4]; float ss = 0.f;
; #pragma unroll
;     for (int i = 0; i < 4; ++i) { v[i] = *(const float4*)(x + lane * 4 + 256 * i); ss += v[i].x * v[i].x + v[i].y * v[i].y + v[i].z * v[i].z + v[i].w * v[i].w; }
;     ss = wave_sum(ss);
;     const float rs = rsqrtf(ss * (1.f / 1024.f) + 1e-6f);
; #pragma unroll
;     for (int i = 0; i < 4; ++i) {
;       const float4 gg = *(const float4*)(p.norm_pre + lane * 4 + 256 * i);
;       st_bf4(h + (size_t)r * 1024 + lane * 4 + 256 * i, v[i].x * rs * gg.x, v[i].y * rs * gg.y, v[i].z * rs * gg.z, v[i].w * rs * gg.w);
;     }
.LBB0_1781:
	s_or_b64 exec, exec, s[42:43]
	v_lshl_add_u64 v[100:101], v[6:7], 0, v[182:183]
	global_load_dwordx4 v[102:105], v[100:101], off
	global_load_dwordx4 v[106:109], v[4:5], off
	global_load_dwordx4 v[110:113], v[100:101], off offset:1024
	global_load_dwordx4 v[114:117], v[100:101], off offset:2048
	global_load_dwordx4 v[118:121], v[100:101], off offset:3072
	global_load_dwordx4 v[122:125], v[4:5], off offset:1024
	global_load_dwordx4 v[126:129], v[4:5], off offset:2048
	global_load_dwordx4 v[130:133], v[4:5], off offset:3072
	s_nop 0
	v_lshlrev_b64 v[14:15], 11, v[0:1]
	v_lshl_add_u64 v[34:35], v[2:3], 0, v[14:15]
	s_nop 0
	s_nop 0
	s_nop 0
	v_add_u32_e32 v0, s3, v0
	s_waitcnt vmcnt(7)
	v_mov_b32_e32 v32, v103
	v_mov_b32_e32 v30, v102
	s_waitcnt vmcnt(5)
	v_mov_b32_e32 v33, v111
	v_mov_b32_e32 v31, v110
	v_pk_mul_f32 v[32:33], v[32:33], v[32:33]
	v_mov_b32_e32 v26, v104
	v_mov_b32_e32 v27, v112
	v_pk_fma_f32 v[30:31], v[30:31], v[30:31], v[32:33]
	v_mov_b32_e32 v28, v105
	v_mov_b32_e32 v29, v113
	v_pk_fma_f32 v[26:27], v[26:27], v[26:27], v[30:31]
	s_nop 0
	v_pk_fma_f32 v[36:37], v[28:29], v[28:29], v[26:27]
	s_nop 0
	s_nop 0
	v_add_f32_e32 v1, v36, v37
	s_waitcnt vmcnt(4)
	v_mov_b32_e32 v42, v115
	s_waitcnt vmcnt(3)
	v_mov_b32_e32 v43, v119
	v_mov_b32_e32 v40, v114
	v_mov_b32_e32 v41, v118
	v_pk_mul_f32 v[42:43], v[42:43], v[42:43]
	v_mov_b32_e32 v6, v116
	v_mov_b32_e32 v7, v120
	v_pk_fma_f32 v[40:41], v[40:41], v[40:41], v[42:43]
	v_mov_b32_e32 v38, v117
	v_mov_b32_e32 v39, v121
	v_pk_fma_f32 v[6:7], v[6:7], v[6:7], v[40:41]
	s_nop 0
	v_pk_fma_f32 v[6:7], v[38:39], v[38:39], v[6:7]
	s_nop 0
	v_add_f32_e32 v1, v1, v6
	v_add_f32_e32 v1, v1, v7
	v_mov_b32_e32 v6, v1
	s_nop 1
	v_permlane32_swap_b32_e32 v1, v6
	s_waitcnt lgkmcnt(0)
	v_add_f32_e32 v1, v1, v6
	v_mov_b32_e32 v6, v1
	s_nop 1
	v_permlane16_swap_b32_e32 v1, v6
	s_waitcnt lgkmcnt(0)
	v_add_f32_e32 v1, v1, v6
	s_nop 1
	v_mov_b32_dpp v6, v1 row_ror:8 row_mask:0xf bank_mask:0xf
	s_waitcnt lgkmcnt(0)
	v_add_f32_e32 v1, v1, v6
	s_nop 1
	v_mov_b32_dpp v6, v1 row_ror:4 row_mask:0xf bank_mask:0xf
	s_waitcnt lgkmcnt(0)
	v_add_f32_e32 v1, v1, v6
	s_nop 1
	v_mov_b32_dpp v6, v1 quad_perm:[2,3,0,1] row_mask:0xf bank_mask:0xf
	s_waitcnt lgkmcnt(0)
	v_add_f32_e32 v1, v1, v6
	s_nop 1
	v_mov_b32_dpp v6, v1 quad_perm:[1,0,3,2] row_mask:0xf bank_mask:0xf
	s_waitcnt lgkmcnt(0)
	v_add_f32_e32 v1, v1, v6
	v_fmamk_f32 v1, v1, 0x3a800000, v184
	v_cmp_gt_f32_e32 vcc, s33, v1
	v_mul_f32_e32 v6, 0x4b800000, v1
	s_nop 0
	v_cndmask_b32_e32 v1, v1, v6, vcc
	v_rsq_f32_e32 v1, v1
	s_nop 0
	v_mul_f32_e32 v6, 0x45800000, v1
	v_cndmask_b32_e32 v6, v1, v6, vcc
	v_pk_mul_f32 v[14:15], v[102:103], v[6:7] op_sel_hi:[1,0]
	v_pk_mul_f32 v[16:17], v[104:105], v[6:7] op_sel_hi:[1,0]
	v_pk_mul_f32 v[14:15], v[106:107], v[14:15]
	v_pk_mul_f32 v[16:17], v[108:109], v[16:17]
	v_cvt_pk_bf16_f32 v14, v14, v15
	v_cvt_pk_bf16_f32 v15, v16, v17
	global_store_dwordx2 v[34:35], v[14:15], off
	s_nop 0
	v_pk_mul_f32 v[18:19], v[110:111], v[6:7] op_sel_hi:[1,0]
	v_cmp_lt_i32_e32 vcc, s64, v0
	s_or_b64 s[40:41], vcc, s[40:41]
	s_waitcnt vmcnt(2)
	v_pk_mul_f32 v[14:15], v[122:123], v[18:19]
	v_pk_mul_f32 v[18:19], v[112:113], v[6:7] op_sel_hi:[1,0]
	v_cvt_pk_bf16_f32 v14, v14, v15
	v_pk_mul_f32 v[16:17], v[124:125], v[18:19]
	v_pk_mul_f32 v[18:19], v[114:115], v[6:7] op_sel_hi:[1,0]
	v_cvt_pk_bf16_f32 v15, v16, v17
	global_store_dwordx2 v[34:35], v[14:15], off offset:512
	s_nop 0
	s_waitcnt vmcnt(1)
	v_pk_mul_f32 v[14:15], v[18:19], v[126:127]
	v_pk_mul_f32 v[18:19], v[116:117], v[6:7] op_sel_hi:[1,0]
	v_cvt_pk_bf16_f32 v14, v14, v15
	v_pk_mul_f32 v[16:17], v[18:19], v[128:129]
	v_pk_mul_f32 v[18:19], v[118:119], v[6:7] op_sel_hi:[1,0]
	v_cvt_pk_bf16_f32 v15, v16, v17
	global_store_dwordx2 v[34:35], v[14:15], off offset:1024
	s_nop 0
	v_pk_mul_f32 v[6:7], v[120:121], v[6:7] op_sel_hi:[1,0]
	s_waitcnt vmcnt(0)
	v_pk_mul_f32 v[14:15], v[18:19], v[130:131]
	v_pk_mul_f32 v[6:7], v[6:7], v[132:133]
	v_cvt_pk_bf16_f32 v14, v14, v15
	v_cvt_pk_bf16_f32 v15, v6, v7
	global_store_dwordx2 v[34:35], v[14:15], off offset:1536
	v_mov_b32_e32 v16, v132
	v_mov_b32_e32 v17, v133
	v_mov_b32_e32 v20, v108
	v_mov_b32_e32 v21, v109
	v_mov_b32_e32 v22, v110
	v_mov_b32_e32 v23, v111
	v_mov_b32_e32 v24, v112
	v_mov_b32_e32 v25, v113
	v_mov_b32_e32 v26, v114
	v_mov_b32_e32 v27, v115
	v_mov_b32_e32 v28, v116
	v_mov_b32_e32 v29, v117
	v_mov_b32_e32 v30, v118
	v_mov_b32_e32 v31, v119
	v_mov_b32_e32 v32, v120
	v_mov_b32_e32 v33, v121
	s_andn2_b64 exec, exec, s[40:41]
	s_cbranch_execz .LBB0_1786
